# v46: v44 + static s_setprio 1 for waves 4-7 during P3 (FoX/scan), reset at P3 exit
# baseline (speedup 1.0000x reference)
; __global__ void __launch_bounds__(512, 2) fwd_mega(Params P) {
;     ...
;     for (int rep = 0; rep < NREP(3); ++rep)
;     {
;     bool first = true;
;     for (;;) {
;         PHASE_IDS
;         int pr;
;         if (first) { first = false; pr = bid; }
;         else {
;             __syncthreads();
;             if (tid == 0) *s_item = nblk + atomicAdd((int*)(ws + OFF_CTR) + rep, 1);
;             __syncthreads();
;             pr = *s_item;
;         }
;         if (pr >= 64 + 512) break;
;         if (pr < 64) gdn_scan(P, pr * 2 + team, smem, tt);
;         else { const int fj = pr - 64; fox_attn(P, (fj & 31) * 2 + team, 15 - (fj >> 5), smem, tt); }
;     }
.LBB0_529:
	s_or_b64 exec, exec, s[0:1]
	s_add_u32 s4, s80, 0x1d83800
	s_addc_u32 s5, s81, 0
	s_add_u32 s6, s80, 0x6000000
	s_addc_u32 s7, s81, 0
	s_add_u32 s8, s80, 0x8000000
	s_addc_u32 s9, s81, 0
	s_add_u32 s10, s80, 0x6030400
	s_mov_b32 s14, 0
	v_readlane_b32 s92, v255, 46
	v_readlane_b32 s62, v255, 42
	v_readlane_b32 s68, v255, 44
	s_addc_u32 s11, s81, 0
	s_mov_b64 s[0:1], -1
	s_mov_b64 s[12:13], 0
	s_mov_b32 s15, 1
	v_mov_b32_e32 v1, 0
	s_mov_b32 s16, 0x3e38aa3b
	s_mov_b32 s17, 0xf149f2ca
	s_mov_b64 s[18:19], 0x20000
	v_mov_b32_e32 v166, 0x358637bd
	s_movk_i32 s40, 0x1000
	s_mov_b64 s[20:21], 0x400
	s_mov_b32 s41, 0x2002000
	s_mov_b32 s42, 0x2004000
	s_mov_b32 s43, 0x2012000
	s_mov_b32 s46, 0x2014000
	s_mov_b64 s[22:23], 0x4000
	s_mov_b64 s[24:25], 0x8000
	v_mov_b32_e32 v167, 0xf149f2ca
	v_mov_b32_e32 v168, 0xb000000
	v_mov_b32_e32 v169, 0xa000000
	v_readlane_b32 s85, v255, 38
	v_readlane_b32 s86, v255, 37
	v_readlane_b32 s93, v255, 47
	v_readlane_b32 s63, v255, 43
	v_readlane_b32 s69, v255, 45
	s_cmp_ge_u32 s84, 0x100
	s_cbranch_scc0 .Lp3_prio_done
	s_setprio 1
.Lp3_prio_done:
	s_waitcnt lgkmcnt(0)
	s_barrier
	s_branch .LBB0_532

; DI int fresh_tid(int wid_s) { int l; asm volatile("v_mbcnt_lo_u32_b32 %0, -1, 0\n\tv_mbcnt_hi_u32_b32 %0, -1, %0" : "=v"(l)); return wid_s * 64 + l; }
; DI void xcd_barrier(const XcdBarrier& b, const int wid_s) {
;     asm volatile("s_waitcnt vmcnt(0)" ::: "memory");
;     __syncthreads();
;     if (fresh_tid(wid_s) == 0) {
;         unsigned* bar = b.bar;
;         __builtin_amdgcn_s_waitcnt(0);
;         unsigned nloc = b.st[0], nx = b.st[1];
;         if (nloc == 0u) { xcd_barrier_complete(bar, b.x, nloc, nx); b.st[0] = nloc; b.st[1] = nx; }
; __global__ void __launch_bounds__(512, 2) fwd_mega(Params P) {
;     ...
;     }
;     xcd_barrier(xbar, wid_s);
.LBB0_591:
	s_or_b64 exec, exec, s[12:13]
	s_setprio 0
	s_waitcnt vmcnt(0)
	v_readlane_b32 s0, v255, 29
	s_barrier
	v_mbcnt_lo_u32_b32 v0, -1, 0
	v_mbcnt_hi_u32_b32 v0, -1, v0
	s_nop 0
	v_cmp_eq_u32_e32 vcc, s0, v0
	s_and_saveexec_b64 s[0:1], vcc
	s_cbranch_execz .LBB0_643
	s_add_i32 s2, 0, 0x25800
	v_mov_b32_e32 v0, s2
	s_waitcnt vmcnt(0) expcnt(0) lgkmcnt(0)
	ds_read_b32 v2, v0
	s_add_i32 s2, 0, 0x25804
	v_mov_b32_e32 v0, s2
	ds_read_b32 v0, v0
	s_waitcnt lgkmcnt(1)
	v_cmp_ne_u32_e32 vcc, 0, v2
	s_cbranch_vccnz .LBB0_607
	v_readlane_b32 s2, v255, 0
	s_mul_i32 s46, s83, s2
	s_add_u32 s2, s80, 0x1d80200
	s_addc_u32 s3, s81, 0
	s_add_u32 s4, s80, 0x1d80400
	s_addc_u32 s5, s81, 0
	s_add_u32 s6, s80, 0x1d80500
	s_addc_u32 s7, s81, 0
	s_add_u32 s8, s80, 0x1d80600
	s_addc_u32 s9, s81, 0
	s_add_u32 s10, s80, 0x1d80700
	s_addc_u32 s11, s81, 0
	s_add_u32 s12, s80, 0x1d80800
	s_addc_u32 s13, s81, 0
	s_add_u32 s14, s80, 0x1d80900
	s_addc_u32 s15, s81, 0
	s_add_u32 s16, s80, 0x1d80a00
	s_addc_u32 s17, s81, 0
	s_add_u32 s18, s80, 0x1d80b00
	s_addc_u32 s19, s81, 0
	s_add_u32 s20, s80, 0x1d80c00
	s_addc_u32 s21, s81, 0
	s_add_u32 s22, s80, 0x1d80d00
	s_addc_u32 s23, s81, 0
	s_add_u32 s24, s80, 0x1d80e00
	s_addc_u32 s25, s81, 0
	s_add_u32 s26, s80, 0x1d80f00
	s_addc_u32 s27, s81, 0
	s_add_u32 s28, s80, 0x1d81000
	s_addc_u32 s29, s81, 0
	s_add_u32 s30, s80, 0x1d81100
	s_addc_u32 s31, s81, 0
	s_add_u32 s34, s80, 0x1d81200
	s_addc_u32 s35, s81, 0
	s_add_u32 s36, s80, 0x1d81300
	s_mul_i32 s46, s46, s82
	s_addc_u32 s37, s81, 0
	s_mov_b32 s47, 1
	v_mov_b32_e32 v16, 0
	s_branch .LBB0_595
